# pp-GEMM unit schedule rebalanced: CUs 128-191 (which finish in_proj with the slow dt softplus epilogue) take no pp units, CUs <128 take 3
# speedup vs baseline: 1.0253x; 1.0253x over previous
;     __device__ __forceinline__ bool next(int i, pg8::Unit& u) const {
;     ...
;         if (G == 256) { if (c < 192) { if (i >= 2) return false; L = c * 2 + i; } else { if (i >= 10) return false; L = 384 + (c - 192) * 10 + i; } }
;         else { L = i * G + c; if (L >= 1024) return false; }
;         u.pm = L >> 4; u.pn = L & 15; return true;
.LBB0_415:
.LBB0_416:
	s_mul_i32 s15, s2, 3
	s_cmpk_lt_i32 s2, 0x80
	s_cselect_b64 s[12:13], -1, 0
	s_branch .LBB0_418

; #define PG8_STAGE(bufoff, gbase, voff) do { _Pragma("unroll") for (int _i = 0; _i < 2; ++_i) \
;         __builtin_amdgcn_global_load_lds((const unsigned*)((const char*)(gbase) + (voff)[_i]), (PG8_LAS unsigned*)(lds + (bufoff) + ldsw + _i * 8192), 16, 0, 0); } while (0)
; #define PG8_WAIT_V(n) asm volatile("s_waitcnt vmcnt(" #n ")" ::: "memory")
; #define PG8_BAR __builtin_amdgcn_s_barrier()
; template <class Epi, class Sched, bool ALIGN_EPI = false, bool SP2 = false>
; __device__ __forceinline__ void gemm_phase(PG8_LAS unsigned char* lds, const Gemm g, const Sched& S, const Epi& E) {
;     ...
;     const char* cA = (const char*)g.A + (size_t)cur.pm * tstepA; const char* cB = (const char*)g.Bt + (size_t)cur.pn * tstep;
;     S.a_ready(cur);
;     if constexpr (SP2) {
;         PG8_STAGE(PG8_SB(0, 0), cB, voffB); PG8_STAGE(PG8_SB(0, 1), cB + hstep, voffB); PG8_STAGE(PG8_SA(0, 0), cA, voffA); PG8_STAGE(PG8_SA(0, 1), cA + hstep, voffA);
;         if (wr == 1) PG8_BAR;
;         PG8_WAIT_V(2); PG8_BAR;
;         PG8_STAGE(PG8_SB(1, 0), cB + kstep, voffB); PG8_STAGE(PG8_SA(1, 0), cA + kstep, voffA); PG8_STAGE(PG8_SB(1, 1), cB + hstep + kstep, voffB);
;         PG8_WAIT_V(6); PG8_BAR;
;     __device__ __forceinline__ bool next(int i, pg8::Unit& u) const {
;     ...
;         if (G == 256) { if (c < 192) { if (i >= 2) return false; L = c * 2 + i; } else { if (i >= 10) return false; L = 384 + (c - 192) * 10 + i; } }
;         else { L = i * G + c; if (L >= 1024) return false; }
;         u.pm = L >> 4; u.pn = L & 15; return true;
.LBB0_421:
	s_add_u32 s10, s10, 0x4ca00000
	s_addc_u32 s11, s11, 0
	s_lshl_b32 s14, s14, 5
	s_and_b32 s22, s14, 0x60
	s_mov_b64 s[14:15], 0x80
	s_add_i32 m0, s45, 0x18000
	v_lshl_add_u64 v[8:9], v[8:9], 0, s[14:15]
	s_lshl_b32 s17, s16, 13
	s_lshl_b32 s19, s22, 7
	s_waitcnt vmcnt(2)
	s_barrier
	global_load_lds_dwordx4 v[8:9], off
	v_lshl_add_u64 v[6:7], v[6:7], 0, s[14:15]
	s_add_i32 m0, s45, 0x1a000
	s_add_i32 s57, s45, 0x8000
	s_add_i32 s58, s45, 0xa000
	global_load_lds_dwordx4 v[6:7], off
	v_lshl_add_u64 v[2:3], v[2:3], 0, s[14:15]
	s_mov_b32 m0, s57
	s_add_u32 s20, s48, 0x10080
	global_load_lds_dwordx4 v[2:3], off
	v_lshl_add_u64 v[2:3], v[4:5], 0, s[14:15]
	s_mov_b32 m0, s58
	s_addc_u32 s21, s49, 0
	global_load_lds_dwordx4 v[2:3], off
	s_add_i32 m0, s45, 0x1c000
	v_lshl_add_u64 v[2:3], s[20:21], 0, v[130:131]
	global_load_lds_dwordx4 v[2:3], off
	v_lshl_add_u64 v[2:3], s[20:21], 0, v[132:133]
	s_add_i32 m0, s45, 0x1e000
	v_lshlrev_b32_e32 v5, 2, v194
	global_load_lds_dwordx4 v[2:3], off
	v_lshrrev_b32_e32 v2, 1, v0
	v_and_b32_e32 v2, 24, v2
	v_lshlrev_b32_e32 v3, 1, v2
	v_lshl_or_b32 v4, v194, 6, v3
	v_and_b32_e32 v5, 32, v5
	s_cmpk_gt_i32 s2, 0xbf
	v_lshl_or_b32 v134, s16, 6, v194
	v_bitop3_b32 v4, v4, s17, v5 bitop3:0xde
	s_cselect_b64 s[16:17], -1, 0
	s_lshl_b32 s20, s2, 1
	v_or_b32_e32 v1, v3, v1
	s_waitcnt vmcnt(6)
	s_cmpk_lt_u32 s18, 0x100
	v_bitop3_b32 v1, s19, v1, v195 bitop3:0xf6
	s_mul_i32 s60, s2, 10
	s_cselect_b64 s[18:19], -1, 0
	s_add_i32 s62, 0, 0x10000
	s_add_i32 s63, 0, 0x14000
	s_mul_i32 s59, s2, 3
	s_add_i32 s59, s59, 1
	v_or_b32_e32 v135, s22, v2
	s_addk_i32 s60, 0xfa01
	s_add_i32 s61, s2, s74
	v_add_u32_e32 v136, s62, v1
	v_add_u32_e32 v137, s63, v1
	v_add_u32_e32 v138, 0, v4
	s_mov_b64 s[20:21], 0x100
	s_mov_b64 s[22:23], 0x180
	s_mov_b64 s[24:25], 0x100000
	s_mov_b32 s64, 0x100000
	s_mov_b64 s[26:27], 0x120000
	s_mov_b32 s65, 0x120000
	s_mov_b64 s[28:29], 0x140000
	s_mov_b32 s66, 0x140000
	s_mov_b64 s[30:31], 0x160000
	s_mov_b32 s67, 0x160000
	s_barrier
	s_branch .LBB0_424

; template <class Epi, class Sched, bool ALIGN_EPI = false, bool SP2 = false>
; __device__ __forceinline__ void gemm_phase(PG8_LAS unsigned char* lds, const Gemm g, const Sched& S, const Epi& E) {
;     ...
;         const bool has_next = S.next(ui + 1, nxt);
;         const char* nA = has_next ? (const char*)g.A + (size_t)nxt.pm * tstepA : cA; const char* nB = has_next ? (const char*)g.Bt + (size_t)nxt.pn * tstep : cB;
;     __device__ __forceinline__ bool next(int i, pg8::Unit& u) const {
;     ...
;         if (G == 256) { if (c < 192) { if (i >= 2) return false; L = c * 2 + i; } else { if (i >= 10) return false; L = 384 + (c - 192) * 10 + i; } }
;         else { L = i * G + c; if (L >= 1024) return false; }
;         u.pm = L >> 4; u.pn = L & 15; return true;
.LBB0_431:
	s_and_b64 vcc, exec, s[40:41]
	s_cbranch_vccz .LBB0_433
	s_cmp_lt_u32 s35, 2
	s_cselect_b64 s[38:39], -1, 0
	s_add_i32 s37, s59, s35
